# grid barrier: per-CU L1 invalidate issued at arrival (before the wait) instead of after the release is observed
# speedup vs baseline: 1.0168x; 1.0168x over previous
; __device__ __forceinline__ int lane_id() { return (int)__builtin_amdgcn_mbcnt_hi(~0u, __builtin_amdgcn_mbcnt_lo(~0u, 0u)); }
; __device__ __forceinline__ unsigned xb_ld(unsigned* p)              { return __hip_atomic_load(p, __ATOMIC_RELAXED, __HIP_MEMORY_SCOPE_AGENT); }
; __device__ __forceinline__ unsigned xb_add(unsigned* p, unsigned v) { return __hip_atomic_fetch_add(p, v, __ATOMIC_RELAXED, __HIP_MEMORY_SCOPE_AGENT); }
; #define XB_SPIN(cond, bar) do { unsigned _sp = 0; while (cond) { __builtin_amdgcn_s_sleep(1); \
;     if ((++_sp & 255u) == 0u) { if (xb_ld(&(bar)[XB_TMO])) break; if (_sp > XB_SPIN_CAP) { atomicAdd(&(bar)[XB_TMO], 1u); break; } } } } while (0)
; __device__ __forceinline__ void xcd_barrier(const XcdBarrier& b) {
;     asm volatile("s_waitcnt vmcnt(0)" ::: "memory");
;     __syncthreads();
;     if (b.wid == 0 && lane_id() == 0) {
;         unsigned* bar = b.bar;
;         __builtin_amdgcn_s_waitcnt(0);
;         unsigned nloc = b.st[0], nx = b.st[1];
;         if (nloc == 0u) { xcd_barrier_complete(bar, b.x, nloc, nx); b.st[0] = nloc; b.st[1] = nx; }
;         const unsigned old = xb_add(&bar[XB_XSUB(b.x)], 1u);
;         const unsigned gen = old / nloc;
;         if (old + 1u == (gen + 1u) * nloc) {
;             __builtin_amdgcn_fence(__ATOMIC_RELEASE, "agent");
;             asm volatile("s_waitcnt vmcnt(0)" ::: "memory");
;             const unsigned og = xb_add(&bar[XB_TOP], 1u);
;             const unsigned tg = og / nx;
;             if (og + 1u == (tg + 1u) * nx) xb_add(&bar[XB_TOPGEN], 1u);
;             else XB_SPIN(xb_ld(&bar[XB_TOPGEN]) == tg, bar);
;             __builtin_amdgcn_fence(__ATOMIC_ACQUIRE, "agent");
;             xb_add(&bar[XB_XGEN(b.x)], 1u);
;             asm volatile("s_waitcnt vmcnt(0)" ::: "memory");
;         } else {
;             XB_SPIN(xb_ld(&bar[XB_XGEN(b.x)]) == gen, bar);
;             __builtin_amdgcn_fence(__ATOMIC_ACQUIRE, "agent");
;             asm volatile("s_waitcnt vmcnt(0)" ::: "memory");
;         }
.LBB0_59:
	s_lshl_b32 s6, s87, 8
	s_add_u32 s6, s88, s6
	s_addc_u32 s7, s89, 0
	v_mov_b32_e32 v1, 0x1000
	v_mov_b32_e32 v3, 1
	global_atomic_add v3, v1, v3, s[6:7] offset:1024 sc0
	buffer_inv sc1
	v_cvt_f32_u32_e32 v1, v2
	v_sub_u32_e32 v4, 0, v2
	v_rcp_iflag_f32_e32 v1, v1
	s_nop 0
	v_mul_f32_e32 v1, 0x4f7ffffe, v1
	v_cvt_u32_f32_e32 v1, v1
	v_mul_lo_u32 v4, v4, v1
	v_mul_hi_u32 v4, v1, v4
	v_add_u32_e32 v1, v1, v4
	s_waitcnt vmcnt(0)
	v_mul_hi_u32 v1, v3, v1
	v_mul_lo_u32 v4, v1, v2
	v_sub_u32_e32 v4, v3, v4
	v_add_u32_e32 v5, 1, v1
	v_cmp_ge_u32_e32 vcc, v4, v2
	v_add_u32_e32 v3, 1, v3
	s_nop 0
	v_cndmask_b32_e32 v1, v1, v5, vcc
	v_sub_u32_e32 v5, v4, v2
	v_cndmask_b32_e32 v4, v4, v5, vcc
	v_add_u32_e32 v5, 1, v1
	v_cmp_ge_u32_e32 vcc, v4, v2
	s_nop 1
	v_cndmask_b32_e32 v1, v1, v5, vcc
	v_mul_lo_u32 v4, v2, v1
	v_add_u32_e32 v2, v4, v2
	v_cmp_ne_u32_e32 vcc, v3, v2
	s_and_saveexec_b64 s[14:15], vcc
	s_xor_b64 s[14:15], exec, s[14:15]
	s_cbranch_execz .LBB0_73
	s_waitcnt lgkmcnt(0)
	v_mov_b32_e32 v0, 0x2000
	global_load_dword v0, v0, s[6:7] offset:1024 sc1
	s_add_u32 s20, s6, 0x2400
	s_addc_u32 s21, s7, 0
	s_waitcnt vmcnt(0)
	v_cmp_eq_u32_e32 vcc, v0, v1
	s_and_saveexec_b64 s[16:17], vcc
	s_cbranch_execz .LBB0_72
	s_add_u32 s18, s80, 0x10200
	s_addc_u32 s19, s81, 0
	s_mov_b32 s33, 1
	s_mov_b64 s[22:23], 0
	v_mov_b32_e32 v0, 0
	s_branch .LBB0_63

; __device__ __forceinline__ unsigned xb_ld(unsigned* p)              { return __hip_atomic_load(p, __ATOMIC_RELAXED, __HIP_MEMORY_SCOPE_AGENT); }
; #define XB_SPIN(cond, bar) do { unsigned _sp = 0; while (cond) { __builtin_amdgcn_s_sleep(1); \
;     if ((++_sp & 255u) == 0u) { if (xb_ld(&(bar)[XB_TMO])) break; if (_sp > XB_SPIN_CAP) { atomicAdd(&(bar)[XB_TMO], 1u); break; } } } } while (0)
; __device__ __forceinline__ void xcd_barrier(const XcdBarrier& b) {
;     ...
;         } else {
;             XB_SPIN(xb_ld(&bar[XB_XGEN(b.x)]) == gen, bar);
;             __builtin_amdgcn_fence(__ATOMIC_ACQUIRE, "agent");
;             asm volatile("s_waitcnt vmcnt(0)" ::: "memory");
;         }
.LBB0_72:
	s_or_b64 exec, exec, s[16:17]
	s_waitcnt vmcnt(0)
	s_waitcnt vmcnt(0)

; __device__ __forceinline__ unsigned xb_ld(unsigned* p)              { return __hip_atomic_load(p, __ATOMIC_RELAXED, __HIP_MEMORY_SCOPE_AGENT); }
; __device__ __forceinline__ unsigned xb_add(unsigned* p, unsigned v) { return __hip_atomic_fetch_add(p, v, __ATOMIC_RELAXED, __HIP_MEMORY_SCOPE_AGENT); }
; #define XB_SPIN(cond, bar) do { unsigned _sp = 0; while (cond) { __builtin_amdgcn_s_sleep(1); \
;     if ((++_sp & 255u) == 0u) { if (xb_ld(&(bar)[XB_TMO])) break; if (_sp > XB_SPIN_CAP) { atomicAdd(&(bar)[XB_TMO], 1u); break; } } } } while (0)
; __device__ __forceinline__ void xcd_barrier(const XcdBarrier& b) {
;     ...
;         if (old + 1u == (gen + 1u) * nloc) {
;             __builtin_amdgcn_fence(__ATOMIC_RELEASE, "agent");
;             asm volatile("s_waitcnt vmcnt(0)" ::: "memory");
;             const unsigned og = xb_add(&bar[XB_TOP], 1u);
;             const unsigned tg = og / nx;
;             if (og + 1u == (tg + 1u) * nx) xb_add(&bar[XB_TOPGEN], 1u);
;             else XB_SPIN(xb_ld(&bar[XB_TOPGEN]) == tg, bar);
;             __builtin_amdgcn_fence(__ATOMIC_ACQUIRE, "agent");
;             xb_add(&bar[XB_XGEN(b.x)], 1u);
;             asm volatile("s_waitcnt vmcnt(0)" ::: "memory");
.LBB0_90:
	s_or_b64 exec, exec, s[14:15]
	v_mov_b32_e32 v0, 0x2000
	v_mov_b32_e32 v1, 1
	s_waitcnt vmcnt(0)
	global_atomic_add v0, v1, s[6:7] offset:1024
	s_waitcnt vmcnt(0)

; __device__ __forceinline__ int lane_id() { return (int)__builtin_amdgcn_mbcnt_hi(~0u, __builtin_amdgcn_mbcnt_lo(~0u, 0u)); }
; __device__ __forceinline__ unsigned xb_ld(unsigned* p)              { return __hip_atomic_load(p, __ATOMIC_RELAXED, __HIP_MEMORY_SCOPE_AGENT); }
; __device__ __forceinline__ unsigned xb_add(unsigned* p, unsigned v) { return __hip_atomic_fetch_add(p, v, __ATOMIC_RELAXED, __HIP_MEMORY_SCOPE_AGENT); }
; #define XB_SPIN(cond, bar) do { unsigned _sp = 0; while (cond) { __builtin_amdgcn_s_sleep(1); \
;     if ((++_sp & 255u) == 0u) { if (xb_ld(&(bar)[XB_TMO])) break; if (_sp > XB_SPIN_CAP) { atomicAdd(&(bar)[XB_TMO], 1u); break; } } } } while (0)
; __device__ __forceinline__ void xcd_barrier(const XcdBarrier& b) {
;     asm volatile("s_waitcnt vmcnt(0)" ::: "memory");
;     __syncthreads();
;     if (b.wid == 0 && lane_id() == 0) {
;         unsigned* bar = b.bar;
;         __builtin_amdgcn_s_waitcnt(0);
;         unsigned nloc = b.st[0], nx = b.st[1];
;         if (nloc == 0u) { xcd_barrier_complete(bar, b.x, nloc, nx); b.st[0] = nloc; b.st[1] = nx; }
;         const unsigned old = xb_add(&bar[XB_XSUB(b.x)], 1u);
;         const unsigned gen = old / nloc;
;         if (old + 1u == (gen + 1u) * nloc) {
;             __builtin_amdgcn_fence(__ATOMIC_RELEASE, "agent");
;             asm volatile("s_waitcnt vmcnt(0)" ::: "memory");
;             const unsigned og = xb_add(&bar[XB_TOP], 1u);
;             const unsigned tg = og / nx;
;             if (og + 1u == (tg + 1u) * nx) xb_add(&bar[XB_TOPGEN], 1u);
;             else XB_SPIN(xb_ld(&bar[XB_TOPGEN]) == tg, bar);
;             __builtin_amdgcn_fence(__ATOMIC_ACQUIRE, "agent");
;             xb_add(&bar[XB_XGEN(b.x)], 1u);
;             asm volatile("s_waitcnt vmcnt(0)" ::: "memory");
;         } else {
;             XB_SPIN(xb_ld(&bar[XB_XGEN(b.x)]) == gen, bar);
;             __builtin_amdgcn_fence(__ATOMIC_ACQUIRE, "agent");
;             asm volatile("s_waitcnt vmcnt(0)" ::: "memory");
;         }
.LBB0_527:
	s_lshl_b32 s4, s87, 8
	s_add_u32 s4, s88, s4
	s_addc_u32 s5, s89, 0
	v_mov_b32_e32 v1, 0x1000
	v_mov_b32_e32 v3, 1
	global_atomic_add v3, v1, v3, s[4:5] offset:1024 sc0
	buffer_inv sc1
	v_cvt_f32_u32_e32 v1, v2
	v_sub_u32_e32 v4, 0, v2
	v_rcp_iflag_f32_e32 v1, v1
	s_nop 0
	v_mul_f32_e32 v1, 0x4f7ffffe, v1
	v_cvt_u32_f32_e32 v1, v1
	v_mul_lo_u32 v4, v4, v1
	v_mul_hi_u32 v4, v1, v4
	v_add_u32_e32 v1, v1, v4
	s_waitcnt vmcnt(0)
	v_mul_hi_u32 v1, v3, v1
	v_mul_lo_u32 v4, v1, v2
	v_sub_u32_e32 v4, v3, v4
	v_add_u32_e32 v5, 1, v1
	v_cmp_ge_u32_e32 vcc, v4, v2
	v_add_u32_e32 v3, 1, v3
	s_nop 0
	v_cndmask_b32_e32 v1, v1, v5, vcc
	v_sub_u32_e32 v5, v4, v2
	v_cndmask_b32_e32 v4, v4, v5, vcc
	v_add_u32_e32 v5, 1, v1
	v_cmp_ge_u32_e32 vcc, v4, v2
	s_nop 1
	v_cndmask_b32_e32 v1, v1, v5, vcc
	v_mul_lo_u32 v4, v2, v1
	v_add_u32_e32 v2, v4, v2
	v_cmp_ne_u32_e32 vcc, v3, v2
	s_and_saveexec_b64 s[6:7], vcc
	s_xor_b64 s[6:7], exec, s[6:7]
	s_cbranch_execz .LBB0_541
	s_waitcnt lgkmcnt(0)
	v_mov_b32_e32 v0, 0x2000
	global_load_dword v0, v0, s[4:5] offset:1024 sc1
	s_add_u32 s12, s4, 0x2400
	s_addc_u32 s13, s5, 0
	s_waitcnt vmcnt(0)
	v_cmp_eq_u32_e32 vcc, v0, v1
	s_and_saveexec_b64 s[8:9], vcc
	s_cbranch_execz .LBB0_540
	s_add_u32 s10, s80, 0x10200
	s_addc_u32 s11, s81, 0
	s_mov_b32 s24, 1
	s_mov_b64 s[14:15], 0
	v_mov_b32_e32 v0, 0
	s_branch .LBB0_531

; __device__ __forceinline__ unsigned xb_ld(unsigned* p)              { return __hip_atomic_load(p, __ATOMIC_RELAXED, __HIP_MEMORY_SCOPE_AGENT); }
; #define XB_SPIN(cond, bar) do { unsigned _sp = 0; while (cond) { __builtin_amdgcn_s_sleep(1); \
;     if ((++_sp & 255u) == 0u) { if (xb_ld(&(bar)[XB_TMO])) break; if (_sp > XB_SPIN_CAP) { atomicAdd(&(bar)[XB_TMO], 1u); break; } } } } while (0)
; __device__ __forceinline__ void xcd_barrier(const XcdBarrier& b) {
;     ...
;         } else {
;             XB_SPIN(xb_ld(&bar[XB_XGEN(b.x)]) == gen, bar);
;             __builtin_amdgcn_fence(__ATOMIC_ACQUIRE, "agent");
;             asm volatile("s_waitcnt vmcnt(0)" ::: "memory");
;         }
.LBB0_540:
	s_or_b64 exec, exec, s[8:9]
	s_waitcnt vmcnt(0)
	s_waitcnt vmcnt(0)

; __device__ __forceinline__ unsigned xb_ld(unsigned* p)              { return __hip_atomic_load(p, __ATOMIC_RELAXED, __HIP_MEMORY_SCOPE_AGENT); }
; __device__ __forceinline__ unsigned xb_add(unsigned* p, unsigned v) { return __hip_atomic_fetch_add(p, v, __ATOMIC_RELAXED, __HIP_MEMORY_SCOPE_AGENT); }
; #define XB_SPIN(cond, bar) do { unsigned _sp = 0; while (cond) { __builtin_amdgcn_s_sleep(1); \
;     if ((++_sp & 255u) == 0u) { if (xb_ld(&(bar)[XB_TMO])) break; if (_sp > XB_SPIN_CAP) { atomicAdd(&(bar)[XB_TMO], 1u); break; } } } } while (0)
; __device__ __forceinline__ void xcd_barrier(const XcdBarrier& b) {
;     ...
;         if (old + 1u == (gen + 1u) * nloc) {
;             __builtin_amdgcn_fence(__ATOMIC_RELEASE, "agent");
;             asm volatile("s_waitcnt vmcnt(0)" ::: "memory");
;             const unsigned og = xb_add(&bar[XB_TOP], 1u);
;             const unsigned tg = og / nx;
;             if (og + 1u == (tg + 1u) * nx) xb_add(&bar[XB_TOPGEN], 1u);
;             else XB_SPIN(xb_ld(&bar[XB_TOPGEN]) == tg, bar);
;             __builtin_amdgcn_fence(__ATOMIC_ACQUIRE, "agent");
;             xb_add(&bar[XB_XGEN(b.x)], 1u);
;             asm volatile("s_waitcnt vmcnt(0)" ::: "memory");
.LBB0_558:
	s_or_b64 exec, exec, s[6:7]
	v_mov_b32_e32 v0, 0x2000
	v_mov_b32_e32 v1, 1
	s_waitcnt vmcnt(0)
	global_atomic_add v0, v1, s[4:5] offset:1024
	s_waitcnt vmcnt(0)
